# plus two-rows-in-flight rmsnorm loops (k=0, k=6, final) with gains loaded once
# baseline (speedup 1.0000x reference)
.LBB2_213:
	v_mov_b32_e32 v0, v146
	v_readlane_b32 s2, v252, 44
	s_waitcnt lgkmcnt(0)
	v_ashrrev_i32_e32 v2, 6, v0
	v_add_u32_e32 v34, s2, v2
	s_movk_i32 s2, 0x2000
	v_cmp_gt_i32_e32 vcc, s2, v34
	s_and_saveexec_b64 s[2:3], vcc
	v_readlane_b32 s8, v254, 41
	v_readlane_b32 s9, v254, 42
	s_cbranch_execz .LBB2_216
	v_and_b32_e32 v4, 63, v0
	v_and_b32_e32 v0, 64, v189
	v_add_u32_e32 v0, 64, v0
	v_xor_b32_e32 v2, 1, v189
	v_cmp_lt_i32_e32 vcc, v2, v0
	v_readlane_b32 s4, v254, 46
	v_readlane_b32 s5, v254, 47
	v_cndmask_b32_e32 v2, v189, v2, vcc
	v_lshlrev_b32_e32 v54, 2, v2
	v_xor_b32_e32 v2, 2, v189
	v_cmp_lt_i32_e32 vcc, v2, v0
	v_readlane_b32 s36, v252, 23
	s_lshl_b64 s[4:5], s[4:5], 13
	v_cndmask_b32_e32 v2, v189, v2, vcc
	v_lshlrev_b32_e32 v55, 2, v2
	v_xor_b32_e32 v2, 4, v189
	v_cmp_lt_i32_e32 vcc, v2, v0
	v_readlane_b32 s42, v252, 29
	v_readlane_b32 s43, v252, 30
	v_cndmask_b32_e32 v2, v189, v2, vcc
	v_lshlrev_b32_e32 v56, 2, v2
	v_xor_b32_e32 v2, 8, v189
	v_cmp_lt_i32_e32 vcc, v2, v0
	s_add_u32 s4, s42, s4
	s_addc_u32 s5, s43, s5
	v_cndmask_b32_e32 v2, v189, v2, vcc
	v_lshlrev_b32_e32 v57, 2, v2
	v_xor_b32_e32 v2, 16, v189
	v_cmp_lt_i32_e32 vcc, v2, v0
	v_mov_b32_e32 v3, v1
	v_ashrrev_i32_e32 v35, 31, v34
	v_cndmask_b32_e32 v2, v189, v2, vcc
	v_lshlrev_b32_e32 v58, 2, v2
	v_xor_b32_e32 v2, 32, v189
	v_cmp_lt_i32_e32 vcc, v2, v0
	v_readlane_b32 s37, v252, 24
	v_readlane_b32 s38, v252, 25
	v_cndmask_b32_e32 v0, v189, v2, vcc
	v_lshlrev_b32_e32 v59, 2, v0
	v_lshlrev_b32_e32 v0, 4, v4
	v_or_b32_e32 v2, 0x1000, v0
	v_lshl_add_u64 v[38:39], s[4:5], 0, v[2:3]
	v_or_b32_e32 v2, 0x1400, v0
	v_lshl_add_u64 v[40:41], s[4:5], 0, v[2:3]
	v_or_b32_e32 v2, 0x1800, v0
	v_lshl_add_u64 v[42:43], s[4:5], 0, v[2:3]
	v_or_b32_e32 v2, 0x1c00, v0
	v_lshl_add_u64 v[36:37], s[4:5], 0, v[0:1]
	v_lshl_add_u64 v[44:45], s[4:5], 0, v[2:3]
	v_lshlrev_b64 v[2:3], 12, v[34:35]
	v_readlane_b32 s4, v254, 48
	v_lshl_or_b32 v2, v4, 3, v2
	v_readlane_b32 s5, v254, 49
	v_readlane_b32 s39, v252, 26
	v_readlane_b32 s40, v252, 27
	v_lshl_add_u64 v[2:3], s[4:5], 0, v[2:3]
	s_mov_b64 s[4:5], 0x1800000
	v_lshl_add_u64 v[46:47], v[2:3], 0, s[4:5]
	v_lshlrev_b64 v[2:3], 13, v[34:35]
	v_readlane_b32 s4, v254, 27
	v_or_b32_e32 v2, v2, v0
	v_readlane_b32 s5, v254, 28
	v_readlane_b32 s41, v252, 28
	v_readlane_b32 s44, v252, 31
	v_lshl_add_u64 v[48:49], s[4:5], 0, v[2:3]
	s_mov_b64 s[4:5], 0
	v_readlane_b32 s45, v252, 32
	v_readlane_b32 s46, v252, 33
	v_readlane_b32 s47, v252, 34
	v_readlane_b32 s48, v252, 35
	v_readlane_b32 s49, v252, 36
	v_readlane_b32 s50, v252, 37
	v_readlane_b32 s51, v252, 38
	global_load_dwordx4 v[64:67], v[36:37], off
	global_load_dwordx4 v[68:71], v[36:37], off offset:1024
	global_load_dwordx4 v[72:75], v[36:37], off offset:2048
	global_load_dwordx4 v[76:79], v[36:37], off offset:3072
	global_load_dwordx4 v[80:83], v[38:39], off
	global_load_dwordx4 v[84:87], v[40:41], off
	global_load_dwordx4 v[88:91], v[42:43], off
	global_load_dwordx4 v[92:95], v[44:45], off
	s_cmpk_lg_u32 s22, 0x800
	s_cbranch_scc1 .Lnorm6_loop
.Lnorm6_loop2:
	global_load_dwordx4 v[96:99], v[48:49], off offset:-4096
	global_load_dwordx4 v[100:103], v[48:49], off offset:-3072
	global_load_dwordx4 v[104:107], v[48:49], off offset:-2048
	global_load_dwordx4 v[108:111], v[48:49], off offset:-1024
	global_load_dwordx4 v[112:115], v[48:49], off
	global_load_dwordx4 v[116:119], v[48:49], off offset:1024
	global_load_dwordx4 v[120:123], v[48:49], off offset:2048
	global_load_dwordx4 v[124:127], v[48:49], off offset:3072
	v_lshl_add_u64 v[48:49], v[48:49], 0, s[20:21]
	v_add_u32_e32 v34, s22, v34
	global_load_dwordx4 v[156:159], v[48:49], off offset:-4096
	global_load_dwordx4 v[160:163], v[48:49], off offset:-3072
	global_load_dwordx4 v[164:167], v[48:49], off offset:-2048
	global_load_dwordx4 v[168:171], v[48:49], off offset:-1024
	global_load_dwordx4 v[172:175], v[48:49], off
	global_load_dwordx4 v[176:179], v[48:49], off offset:1024
	global_load_dwordx4 v[180:183], v[48:49], off offset:2048
	global_load_dwordx4 v[184:187], v[48:49], off offset:3072
	v_lshl_add_u64 v[48:49], v[48:49], 0, s[20:21]
	v_add_u32_e32 v34, s22, v34
	s_movk_i32 s6, 0x1fff
	s_waitcnt vmcnt(8)
	v_mul_f32_e32 v2, v96, v96
	v_mul_f32_e32 v3, v98, v98
	v_fmac_f32_e32 v2, v97, v97
	v_fmac_f32_e32 v3, v99, v99
	v_add_f32_e32 v0, v2, v3
	v_mul_f32_e32 v2, v100, v100
	v_mul_f32_e32 v3, v102, v102
	v_fmac_f32_e32 v2, v101, v101
	v_fmac_f32_e32 v3, v103, v103
	v_add_f32_e32 v2, v2, v3
	v_add_f32_e32 v0, v0, v2
	v_mul_f32_e32 v2, v104, v104
	v_mul_f32_e32 v3, v106, v106
	v_fmac_f32_e32 v2, v105, v105
	v_fmac_f32_e32 v3, v107, v107
	v_add_f32_e32 v2, v2, v3
	v_add_f32_e32 v0, v0, v2
	v_mul_f32_e32 v2, v108, v108
	v_mul_f32_e32 v3, v110, v110
	v_fmac_f32_e32 v2, v109, v109
	v_fmac_f32_e32 v3, v111, v111
	v_add_f32_e32 v2, v2, v3
	v_add_f32_e32 v0, v0, v2
	v_mul_f32_e32 v2, v112, v112
	v_mul_f32_e32 v3, v114, v114
	v_fmac_f32_e32 v2, v113, v113
	v_fmac_f32_e32 v3, v115, v115
	v_add_f32_e32 v2, v2, v3
	v_add_f32_e32 v0, v0, v2
	v_mul_f32_e32 v2, v116, v116
	v_mul_f32_e32 v3, v118, v118
	v_fmac_f32_e32 v2, v117, v117
	v_fmac_f32_e32 v3, v119, v119
	v_add_f32_e32 v2, v2, v3
	v_add_f32_e32 v0, v0, v2
	v_mul_f32_e32 v2, v120, v120
	v_mul_f32_e32 v3, v122, v122
	v_fmac_f32_e32 v2, v121, v121
	v_fmac_f32_e32 v3, v123, v123
	v_add_f32_e32 v2, v2, v3
	v_add_f32_e32 v0, v0, v2
	v_mul_f32_e32 v2, v124, v124
	v_mul_f32_e32 v3, v126, v126
	v_fmac_f32_e32 v2, v125, v125
	v_fmac_f32_e32 v3, v127, v127
	v_add_f32_e32 v2, v2, v3
	v_add_f32_e32 v0, v0, v2
	ds_bpermute_b32 v35, v54, v0
	s_waitcnt lgkmcnt(0)
	v_add_f32_e32 v0, v0, v35
	ds_bpermute_b32 v35, v55, v0
	s_waitcnt lgkmcnt(0)
	v_add_f32_e32 v0, v0, v35
	ds_bpermute_b32 v35, v56, v0
	s_waitcnt lgkmcnt(0)
	v_add_f32_e32 v0, v0, v35
	ds_bpermute_b32 v35, v57, v0
	s_waitcnt lgkmcnt(0)
	v_add_f32_e32 v0, v0, v35
	ds_bpermute_b32 v35, v58, v0
	s_waitcnt lgkmcnt(0)
	v_add_f32_e32 v0, v0, v35
	ds_bpermute_b32 v35, v59, v0
	s_waitcnt lgkmcnt(0)
	v_add_f32_e32 v0, v0, v35
	v_fmamk_f32 v0, v0, 0x3a000000, v147
	v_cmp_gt_f32_e32 vcc, s29, v0
	v_mul_f32_e32 v35, 0x4b800000, v0
	s_nop 0
	v_cndmask_b32_e32 v0, v0, v35, vcc
	v_rsq_f32_e32 v0, v0
	s_nop 0
	v_mul_f32_e32 v35, 0x45800000, v0
	v_cndmask_b32_e32 v0, v0, v35, vcc
	v_mul_f32_e32 v2, v96, v0
	v_mul_f32_e32 v3, v97, v0
	v_mul_f32_e32 v4, v98, v0
	v_mul_f32_e32 v5, v99, v0
	v_mul_f32_e32 v2, v2, v64
	v_mul_f32_e32 v3, v3, v65
	v_mul_f32_e32 v4, v4, v66
	v_mul_f32_e32 v5, v5, v67
	v_cvt_pk_bf16_f32 v128, v2, v3
	v_cvt_pk_bf16_f32 v129, v4, v5
	global_store_dwordx2 v[46:47], v[128:129], off
	v_mul_f32_e32 v2, v100, v0
	v_mul_f32_e32 v3, v101, v0
	v_mul_f32_e32 v4, v102, v0
	v_mul_f32_e32 v5, v103, v0
	v_mul_f32_e32 v2, v2, v68
	v_mul_f32_e32 v3, v3, v69
	v_mul_f32_e32 v4, v4, v70
	v_mul_f32_e32 v5, v5, v71
	v_cvt_pk_bf16_f32 v130, v2, v3
	v_cvt_pk_bf16_f32 v131, v4, v5
	global_store_dwordx2 v[46:47], v[130:131], off offset:512
	v_mul_f32_e32 v2, v104, v0
	v_mul_f32_e32 v3, v105, v0
	v_mul_f32_e32 v4, v106, v0
	v_mul_f32_e32 v5, v107, v0
	v_mul_f32_e32 v2, v2, v72
	v_mul_f32_e32 v3, v3, v73
	v_mul_f32_e32 v4, v4, v74
	v_mul_f32_e32 v5, v5, v75
	v_cvt_pk_bf16_f32 v132, v2, v3
	v_cvt_pk_bf16_f32 v133, v4, v5
	global_store_dwordx2 v[46:47], v[132:133], off offset:1024
	v_mul_f32_e32 v2, v108, v0
	v_mul_f32_e32 v3, v109, v0
	v_mul_f32_e32 v4, v110, v0
	v_mul_f32_e32 v5, v111, v0
	v_mul_f32_e32 v2, v2, v76
	v_mul_f32_e32 v3, v3, v77
	v_mul_f32_e32 v4, v4, v78
	v_mul_f32_e32 v5, v5, v79
	v_cvt_pk_bf16_f32 v134, v2, v3
	v_cvt_pk_bf16_f32 v135, v4, v5
	global_store_dwordx2 v[46:47], v[134:135], off offset:1536
	v_mul_f32_e32 v2, v112, v0
	v_mul_f32_e32 v3, v113, v0
	v_mul_f32_e32 v4, v114, v0
	v_mul_f32_e32 v5, v115, v0
	v_mul_f32_e32 v2, v2, v80
	v_mul_f32_e32 v3, v3, v81
	v_mul_f32_e32 v4, v4, v82
	v_mul_f32_e32 v5, v5, v83
	v_cvt_pk_bf16_f32 v136, v2, v3
	v_cvt_pk_bf16_f32 v137, v4, v5
	global_store_dwordx2 v[46:47], v[136:137], off offset:2048
	v_mul_f32_e32 v2, v116, v0
	v_mul_f32_e32 v3, v117, v0
	v_mul_f32_e32 v4, v118, v0
	v_mul_f32_e32 v5, v119, v0
	v_mul_f32_e32 v2, v2, v84
	v_mul_f32_e32 v3, v3, v85
	v_mul_f32_e32 v4, v4, v86
	v_mul_f32_e32 v5, v5, v87
	v_cvt_pk_bf16_f32 v138, v2, v3
	v_cvt_pk_bf16_f32 v139, v4, v5
	global_store_dwordx2 v[46:47], v[138:139], off offset:2560
	v_mul_f32_e32 v2, v120, v0
	v_mul_f32_e32 v3, v121, v0
	v_mul_f32_e32 v4, v122, v0
	v_mul_f32_e32 v5, v123, v0
	v_mul_f32_e32 v2, v2, v88
	v_mul_f32_e32 v3, v3, v89
	v_mul_f32_e32 v4, v4, v90
	v_mul_f32_e32 v5, v5, v91
	v_cvt_pk_bf16_f32 v140, v2, v3
	v_cvt_pk_bf16_f32 v141, v4, v5
	global_store_dwordx2 v[46:47], v[140:141], off offset:3072
	v_mul_f32_e32 v2, v124, v0
	v_mul_f32_e32 v3, v125, v0
	v_mul_f32_e32 v4, v126, v0
	v_mul_f32_e32 v5, v127, v0
	v_mul_f32_e32 v2, v2, v92
	v_mul_f32_e32 v3, v3, v93
	v_mul_f32_e32 v4, v4, v94
	v_mul_f32_e32 v5, v5, v95
	v_cvt_pk_bf16_f32 v142, v2, v3
	v_cvt_pk_bf16_f32 v143, v4, v5
	global_store_dwordx2 v[46:47], v[142:143], off offset:3584
	v_lshl_add_u64 v[46:47], v[46:47], 0, s[8:9]
	s_waitcnt vmcnt(8)
	v_mul_f32_e32 v2, v156, v156
	v_mul_f32_e32 v3, v158, v158
	v_fmac_f32_e32 v2, v157, v157
	v_fmac_f32_e32 v3, v159, v159
	v_add_f32_e32 v0, v2, v3
	v_mul_f32_e32 v2, v160, v160
	v_mul_f32_e32 v3, v162, v162
	v_fmac_f32_e32 v2, v161, v161
	v_fmac_f32_e32 v3, v163, v163
	v_add_f32_e32 v2, v2, v3
	v_add_f32_e32 v0, v0, v2
	v_mul_f32_e32 v2, v164, v164
	v_mul_f32_e32 v3, v166, v166
	v_fmac_f32_e32 v2, v165, v165
	v_fmac_f32_e32 v3, v167, v167
	v_add_f32_e32 v2, v2, v3
	v_add_f32_e32 v0, v0, v2
	v_mul_f32_e32 v2, v168, v168
	v_mul_f32_e32 v3, v170, v170
	v_fmac_f32_e32 v2, v169, v169
	v_fmac_f32_e32 v3, v171, v171
	v_add_f32_e32 v2, v2, v3
	v_add_f32_e32 v0, v0, v2
	v_mul_f32_e32 v2, v172, v172
	v_mul_f32_e32 v3, v174, v174
	v_fmac_f32_e32 v2, v173, v173
	v_fmac_f32_e32 v3, v175, v175
	v_add_f32_e32 v2, v2, v3
	v_add_f32_e32 v0, v0, v2
	v_mul_f32_e32 v2, v176, v176
	v_mul_f32_e32 v3, v178, v178
	v_fmac_f32_e32 v2, v177, v177
	v_fmac_f32_e32 v3, v179, v179
	v_add_f32_e32 v2, v2, v3
	v_add_f32_e32 v0, v0, v2
	v_mul_f32_e32 v2, v180, v180
	v_mul_f32_e32 v3, v182, v182
	v_fmac_f32_e32 v2, v181, v181
	v_fmac_f32_e32 v3, v183, v183
	v_add_f32_e32 v2, v2, v3
	v_add_f32_e32 v0, v0, v2
	v_mul_f32_e32 v2, v184, v184
	v_mul_f32_e32 v3, v186, v186
	v_fmac_f32_e32 v2, v185, v185
	v_fmac_f32_e32 v3, v187, v187
	v_add_f32_e32 v2, v2, v3
	v_add_f32_e32 v0, v0, v2
	ds_bpermute_b32 v35, v54, v0
	s_waitcnt lgkmcnt(0)
	v_add_f32_e32 v0, v0, v35
	ds_bpermute_b32 v35, v55, v0
	s_waitcnt lgkmcnt(0)
	v_add_f32_e32 v0, v0, v35
	ds_bpermute_b32 v35, v56, v0
	s_waitcnt lgkmcnt(0)
	v_add_f32_e32 v0, v0, v35
	ds_bpermute_b32 v35, v57, v0
	s_waitcnt lgkmcnt(0)
	v_add_f32_e32 v0, v0, v35
	ds_bpermute_b32 v35, v58, v0
	s_waitcnt lgkmcnt(0)
	v_add_f32_e32 v0, v0, v35
	ds_bpermute_b32 v35, v59, v0
	s_waitcnt lgkmcnt(0)
	v_add_f32_e32 v0, v0, v35
	v_fmamk_f32 v0, v0, 0x3a000000, v147
	v_cmp_gt_f32_e32 vcc, s29, v0
	v_mul_f32_e32 v35, 0x4b800000, v0
	s_nop 0
	v_cndmask_b32_e32 v0, v0, v35, vcc
	v_rsq_f32_e32 v0, v0
	s_nop 0
	v_mul_f32_e32 v35, 0x45800000, v0
	v_cndmask_b32_e32 v0, v0, v35, vcc
	v_mul_f32_e32 v2, v156, v0
	v_mul_f32_e32 v3, v157, v0
	v_mul_f32_e32 v4, v158, v0
	v_mul_f32_e32 v5, v159, v0
	v_mul_f32_e32 v2, v2, v64
	v_mul_f32_e32 v3, v3, v65
	v_mul_f32_e32 v4, v4, v66
	v_mul_f32_e32 v5, v5, v67
	v_cvt_pk_bf16_f32 v192, v2, v3
	v_cvt_pk_bf16_f32 v193, v4, v5
	global_store_dwordx2 v[46:47], v[192:193], off
	v_mul_f32_e32 v2, v160, v0
	v_mul_f32_e32 v3, v161, v0
	v_mul_f32_e32 v4, v162, v0
	v_mul_f32_e32 v5, v163, v0
	v_mul_f32_e32 v2, v2, v68
	v_mul_f32_e32 v3, v3, v69
	v_mul_f32_e32 v4, v4, v70
	v_mul_f32_e32 v5, v5, v71
	v_cvt_pk_bf16_f32 v194, v2, v3
	v_cvt_pk_bf16_f32 v195, v4, v5
	global_store_dwordx2 v[46:47], v[194:195], off offset:512
	v_mul_f32_e32 v2, v164, v0
	v_mul_f32_e32 v3, v165, v0
	v_mul_f32_e32 v4, v166, v0
	v_mul_f32_e32 v5, v167, v0
	v_mul_f32_e32 v2, v2, v72
	v_mul_f32_e32 v3, v3, v73
	v_mul_f32_e32 v4, v4, v74
	v_mul_f32_e32 v5, v5, v75
	v_cvt_pk_bf16_f32 v196, v2, v3
	v_cvt_pk_bf16_f32 v197, v4, v5
	global_store_dwordx2 v[46:47], v[196:197], off offset:1024
	v_mul_f32_e32 v2, v168, v0
	v_mul_f32_e32 v3, v169, v0
	v_mul_f32_e32 v4, v170, v0
	v_mul_f32_e32 v5, v171, v0
	v_mul_f32_e32 v2, v2, v76
	v_mul_f32_e32 v3, v3, v77
	v_mul_f32_e32 v4, v4, v78
	v_mul_f32_e32 v5, v5, v79
	v_cvt_pk_bf16_f32 v198, v2, v3
	v_cvt_pk_bf16_f32 v199, v4, v5
	global_store_dwordx2 v[46:47], v[198:199], off offset:1536
	v_mul_f32_e32 v2, v172, v0
	v_mul_f32_e32 v3, v173, v0
	v_mul_f32_e32 v4, v174, v0
	v_mul_f32_e32 v5, v175, v0
	v_mul_f32_e32 v2, v2, v80
	v_mul_f32_e32 v3, v3, v81
	v_mul_f32_e32 v4, v4, v82
	v_mul_f32_e32 v5, v5, v83
	v_cvt_pk_bf16_f32 v200, v2, v3
	v_cvt_pk_bf16_f32 v201, v4, v5
	global_store_dwordx2 v[46:47], v[200:201], off offset:2048
	v_mul_f32_e32 v2, v176, v0
	v_mul_f32_e32 v3, v177, v0
	v_mul_f32_e32 v4, v178, v0
	v_mul_f32_e32 v5, v179, v0
	v_mul_f32_e32 v2, v2, v84
	v_mul_f32_e32 v3, v3, v85
	v_mul_f32_e32 v4, v4, v86
	v_mul_f32_e32 v5, v5, v87
	v_cvt_pk_bf16_f32 v202, v2, v3
	v_cvt_pk_bf16_f32 v203, v4, v5
	global_store_dwordx2 v[46:47], v[202:203], off offset:2560
	v_mul_f32_e32 v2, v180, v0
	v_mul_f32_e32 v3, v181, v0
	v_mul_f32_e32 v4, v182, v0
	v_mul_f32_e32 v5, v183, v0
	v_mul_f32_e32 v2, v2, v88
	v_mul_f32_e32 v3, v3, v89
	v_mul_f32_e32 v4, v4, v90
	v_mul_f32_e32 v5, v5, v91
	v_cvt_pk_bf16_f32 v204, v2, v3
	v_cvt_pk_bf16_f32 v205, v4, v5
	global_store_dwordx2 v[46:47], v[204:205], off offset:3072
	v_mul_f32_e32 v2, v184, v0
	v_mul_f32_e32 v3, v185, v0
	v_mul_f32_e32 v4, v186, v0
	v_mul_f32_e32 v5, v187, v0
	v_mul_f32_e32 v2, v2, v92
	v_mul_f32_e32 v3, v3, v93
	v_mul_f32_e32 v4, v4, v94
	v_mul_f32_e32 v5, v5, v95
	v_cvt_pk_bf16_f32 v206, v2, v3
	v_cvt_pk_bf16_f32 v207, v4, v5
	global_store_dwordx2 v[46:47], v[206:207], off offset:3584
	v_lshl_add_u64 v[46:47], v[46:47], 0, s[8:9]
	v_cmp_lt_i32_e32 vcc, s6, v34
	s_or_b64 s[4:5], vcc, s[4:5]
	s_andn2_b64 exec, exec, s[4:5]
	s_cbranch_execnz .Lnorm6_loop2
	s_branch .Lnorm6_done

.Lnorm6_done:
.LBB2_216:
	s_or_b64 exec, exec, s[2:3]

.Lnk_loop:
	s_mov_b32 s3, 0x1800000
	s_mov_b64 s[4:5], 0x2000
	global_load_dwordx4 v[156:159], v[64:65], off offset:-4096
	global_load_dwordx4 v[160:163], v[64:65], off offset:-3072
	global_load_dwordx4 v[164:167], v[64:65], off offset:-2048
	global_load_dwordx4 v[168:171], v[64:65], off offset:-1024
	global_load_dwordx4 v[172:175], v[64:65], off
	global_load_dwordx4 v[176:179], v[64:65], off offset:1024
	global_load_dwordx4 v[180:183], v[64:65], off offset:2048
	global_load_dwordx4 v[184:187], v[64:65], off offset:3072
	v_lshl_add_u64 v[64:65], v[64:65], 0, s[4:5]
	global_load_dwordx4 v[192:195], v[64:65], off offset:-4096
	global_load_dwordx4 v[196:199], v[64:65], off offset:-3072
	global_load_dwordx4 v[200:203], v[64:65], off offset:-2048
	global_load_dwordx4 v[204:207], v[64:65], off offset:-1024
	global_load_dwordx4 v[208:211], v[64:65], off
	global_load_dwordx4 v[212:215], v[64:65], off offset:1024
	global_load_dwordx4 v[216:219], v[64:65], off offset:2048
	global_load_dwordx4 v[220:223], v[64:65], off offset:3072
	v_lshl_add_u64 v[64:65], v[64:65], 0, s[4:5]
	v_lshl_add_u64 v[30:31], v[62:63], 0, s[0:1]
	v_add_co_u32_e32 v30, vcc, s3, v30
	s_nop 1
	v_addc_co_u32_e32 v31, vcc, 0, v31, vcc
	s_waitcnt vmcnt(8)
	v_mul_f32_e32 v2, v156, v156
	v_mul_f32_e32 v3, v158, v158
	v_fmac_f32_e32 v2, v157, v157
	v_fmac_f32_e32 v3, v159, v159
	v_add_f32_e32 v0, v2, v3
	v_mul_f32_e32 v2, v160, v160
	v_mul_f32_e32 v3, v162, v162
	v_fmac_f32_e32 v2, v161, v161
	v_fmac_f32_e32 v3, v163, v163
	v_add_f32_e32 v2, v2, v3
	v_add_f32_e32 v0, v0, v2
	v_mul_f32_e32 v2, v164, v164
	v_mul_f32_e32 v3, v166, v166
	v_fmac_f32_e32 v2, v165, v165
	v_fmac_f32_e32 v3, v167, v167
	v_add_f32_e32 v2, v2, v3
	v_add_f32_e32 v0, v0, v2
	v_mul_f32_e32 v2, v168, v168
	v_mul_f32_e32 v3, v170, v170
	v_fmac_f32_e32 v2, v169, v169
	v_fmac_f32_e32 v3, v171, v171
	v_add_f32_e32 v2, v2, v3
	v_add_f32_e32 v0, v0, v2
	v_mul_f32_e32 v2, v172, v172
	v_mul_f32_e32 v3, v174, v174
	v_fmac_f32_e32 v2, v173, v173
	v_fmac_f32_e32 v3, v175, v175
	v_add_f32_e32 v2, v2, v3
	v_add_f32_e32 v0, v0, v2
	v_mul_f32_e32 v2, v176, v176
	v_mul_f32_e32 v3, v178, v178
	v_fmac_f32_e32 v2, v177, v177
	v_fmac_f32_e32 v3, v179, v179
	v_add_f32_e32 v2, v2, v3
	v_add_f32_e32 v0, v0, v2
	v_mul_f32_e32 v2, v180, v180
	v_mul_f32_e32 v3, v182, v182
	v_fmac_f32_e32 v2, v181, v181
	v_fmac_f32_e32 v3, v183, v183
	v_add_f32_e32 v2, v2, v3
	v_add_f32_e32 v0, v0, v2
	v_mul_f32_e32 v2, v184, v184
	v_mul_f32_e32 v3, v186, v186
	v_fmac_f32_e32 v2, v185, v185
	v_fmac_f32_e32 v3, v187, v187
	v_add_f32_e32 v2, v2, v3
	v_add_f32_e32 v0, v0, v2
	ds_bpermute_b32 v78, v68, v0
	s_waitcnt lgkmcnt(0)
	v_add_f32_e32 v0, v0, v78
	ds_bpermute_b32 v78, v69, v0
	s_waitcnt lgkmcnt(0)
	v_add_f32_e32 v0, v0, v78
	ds_bpermute_b32 v78, v70, v0
	s_waitcnt lgkmcnt(0)
	v_add_f32_e32 v0, v0, v78
	ds_bpermute_b32 v78, v71, v0
	s_waitcnt lgkmcnt(0)
	v_add_f32_e32 v0, v0, v78
	ds_bpermute_b32 v78, v72, v0
	s_waitcnt lgkmcnt(0)
	v_add_f32_e32 v0, v0, v78
	ds_bpermute_b32 v78, v73, v0
	s_waitcnt lgkmcnt(0)
	v_add_f32_e32 v0, v0, v78
	v_fmamk_f32 v0, v0, 0x3a000000, v147
	v_cmp_gt_f32_e32 vcc, s29, v0
	v_mul_f32_e32 v78, 0x4b800000, v0
	s_nop 0
	v_cndmask_b32_e32 v0, v0, v78, vcc
	v_rsq_f32_e32 v0, v0
	s_nop 0
	v_mul_f32_e32 v78, 0x45800000, v0
	v_cndmask_b32_e32 v0, v0, v78, vcc
	v_mul_f32_e32 v2, v156, v0
	v_mul_f32_e32 v3, v157, v0
	v_mul_f32_e32 v4, v158, v0
	v_mul_f32_e32 v5, v159, v0
	v_mul_f32_e32 v2, v2, v88
	v_mul_f32_e32 v3, v3, v89
	v_mul_f32_e32 v4, v4, v90
	v_mul_f32_e32 v5, v5, v91
	v_cvt_pk_bf16_f32 v224, v2, v3
	v_cvt_pk_bf16_f32 v225, v4, v5
	global_store_dwordx2 v[30:31], v[224:225], off
	ds_write_b64 v55, v[224:225]
	v_mul_f32_e32 v2, v160, v0
	v_mul_f32_e32 v3, v161, v0
	v_mul_f32_e32 v4, v162, v0
	v_mul_f32_e32 v5, v163, v0
	v_mul_f32_e32 v2, v2, v92
	v_mul_f32_e32 v3, v3, v93
	v_mul_f32_e32 v4, v4, v94
	v_mul_f32_e32 v5, v5, v95
	v_cvt_pk_bf16_f32 v226, v2, v3
	v_cvt_pk_bf16_f32 v227, v4, v5
	global_store_dwordx2 v[30:31], v[226:227], off offset:512
	ds_write_b64 v55, v[226:227] offset:512
	v_mul_f32_e32 v2, v164, v0
	v_mul_f32_e32 v3, v165, v0
	v_mul_f32_e32 v4, v166, v0
	v_mul_f32_e32 v5, v167, v0
	v_mul_f32_e32 v2, v2, v96
	v_mul_f32_e32 v3, v3, v97
	v_mul_f32_e32 v4, v4, v98
	v_mul_f32_e32 v5, v5, v99
	v_cvt_pk_bf16_f32 v228, v2, v3
	v_cvt_pk_bf16_f32 v229, v4, v5
	global_store_dwordx2 v[30:31], v[228:229], off offset:1024
	ds_write_b64 v55, v[228:229] offset:1024
	v_mul_f32_e32 v2, v168, v0
	v_mul_f32_e32 v3, v169, v0
	v_mul_f32_e32 v4, v170, v0
	v_mul_f32_e32 v5, v171, v0
	v_mul_f32_e32 v2, v2, v100
	v_mul_f32_e32 v3, v3, v101
	v_mul_f32_e32 v4, v4, v102
	v_mul_f32_e32 v5, v5, v103
	v_cvt_pk_bf16_f32 v230, v2, v3
	v_cvt_pk_bf16_f32 v231, v4, v5
	global_store_dwordx2 v[30:31], v[230:231], off offset:1536
	ds_write_b64 v55, v[230:231] offset:1536
	v_mul_f32_e32 v2, v172, v0
	v_mul_f32_e32 v3, v173, v0
	v_mul_f32_e32 v4, v174, v0
	v_mul_f32_e32 v5, v175, v0
	v_mul_f32_e32 v2, v2, v104
	v_mul_f32_e32 v3, v3, v105
	v_mul_f32_e32 v4, v4, v106
	v_mul_f32_e32 v5, v5, v107
	v_cvt_pk_bf16_f32 v232, v2, v3
	v_cvt_pk_bf16_f32 v233, v4, v5
	global_store_dwordx2 v[30:31], v[232:233], off offset:2048
	ds_write_b64 v55, v[232:233] offset:2048
	v_mul_f32_e32 v2, v176, v0
	v_mul_f32_e32 v3, v177, v0
	v_mul_f32_e32 v4, v178, v0
	v_mul_f32_e32 v5, v179, v0
	v_mul_f32_e32 v2, v2, v108
	v_mul_f32_e32 v3, v3, v109
	v_mul_f32_e32 v4, v4, v110
	v_mul_f32_e32 v5, v5, v111
	v_cvt_pk_bf16_f32 v234, v2, v3
	v_cvt_pk_bf16_f32 v235, v4, v5
	global_store_dwordx2 v[30:31], v[234:235], off offset:2560
	ds_write_b64 v55, v[234:235] offset:2560
	v_mul_f32_e32 v2, v180, v0
	v_mul_f32_e32 v3, v181, v0
	v_mul_f32_e32 v4, v182, v0
	v_mul_f32_e32 v5, v183, v0
	v_mul_f32_e32 v2, v2, v112
	v_mul_f32_e32 v3, v3, v113
	v_mul_f32_e32 v4, v4, v114
	v_mul_f32_e32 v5, v5, v115
	v_cvt_pk_bf16_f32 v236, v2, v3
	v_cvt_pk_bf16_f32 v237, v4, v5
	global_store_dwordx2 v[30:31], v[236:237], off offset:3072
	ds_write_b64 v55, v[236:237] offset:3072
	v_mul_f32_e32 v2, v184, v0
	v_mul_f32_e32 v3, v185, v0
	v_mul_f32_e32 v4, v186, v0
	v_mul_f32_e32 v5, v187, v0
	v_mul_f32_e32 v2, v2, v116
	v_mul_f32_e32 v3, v3, v117
	v_mul_f32_e32 v4, v4, v118
	v_mul_f32_e32 v5, v5, v119
	v_cvt_pk_bf16_f32 v238, v2, v3
	v_cvt_pk_bf16_f32 v239, v4, v5
	global_store_dwordx2 v[30:31], v[238:239], off offset:3584
	ds_write_b64 v55, v[238:239] offset:3584
	s_add_u32 s0, s0, 0x1000
	s_addc_u32 s1, s1, 0
	v_add_u32_e32 v55, 0x1010, v55
	v_lshl_add_u64 v[30:31], v[62:63], 0, s[0:1]
	v_add_co_u32_e32 v30, vcc, s3, v30
	s_nop 1
	v_addc_co_u32_e32 v31, vcc, 0, v31, vcc
	s_waitcnt vmcnt(8)
	v_mul_f32_e32 v2, v192, v192
	v_mul_f32_e32 v3, v194, v194
	v_fmac_f32_e32 v2, v193, v193
	v_fmac_f32_e32 v3, v195, v195
	v_add_f32_e32 v0, v2, v3
	v_mul_f32_e32 v2, v196, v196
	v_mul_f32_e32 v3, v198, v198
	v_fmac_f32_e32 v2, v197, v197
	v_fmac_f32_e32 v3, v199, v199
	v_add_f32_e32 v2, v2, v3
	v_add_f32_e32 v0, v0, v2
	v_mul_f32_e32 v2, v200, v200
	v_mul_f32_e32 v3, v202, v202
	v_fmac_f32_e32 v2, v201, v201
	v_fmac_f32_e32 v3, v203, v203
	v_add_f32_e32 v2, v2, v3
	v_add_f32_e32 v0, v0, v2
	v_mul_f32_e32 v2, v204, v204
	v_mul_f32_e32 v3, v206, v206
	v_fmac_f32_e32 v2, v205, v205
	v_fmac_f32_e32 v3, v207, v207
	v_add_f32_e32 v2, v2, v3
	v_add_f32_e32 v0, v0, v2
	v_mul_f32_e32 v2, v208, v208
	v_mul_f32_e32 v3, v210, v210
	v_fmac_f32_e32 v2, v209, v209
	v_fmac_f32_e32 v3, v211, v211
	v_add_f32_e32 v2, v2, v3
	v_add_f32_e32 v0, v0, v2
	v_mul_f32_e32 v2, v212, v212
	v_mul_f32_e32 v3, v214, v214
	v_fmac_f32_e32 v2, v213, v213
	v_fmac_f32_e32 v3, v215, v215
	v_add_f32_e32 v2, v2, v3
	v_add_f32_e32 v0, v0, v2
	v_mul_f32_e32 v2, v216, v216
	v_mul_f32_e32 v3, v218, v218
	v_fmac_f32_e32 v2, v217, v217
	v_fmac_f32_e32 v3, v219, v219
	v_add_f32_e32 v2, v2, v3
	v_add_f32_e32 v0, v0, v2
	v_mul_f32_e32 v2, v220, v220
	v_mul_f32_e32 v3, v222, v222
	v_fmac_f32_e32 v2, v221, v221
	v_fmac_f32_e32 v3, v223, v223
	v_add_f32_e32 v2, v2, v3
	v_add_f32_e32 v0, v0, v2
	ds_bpermute_b32 v78, v68, v0
	s_waitcnt lgkmcnt(0)
	v_add_f32_e32 v0, v0, v78
	ds_bpermute_b32 v78, v69, v0
	s_waitcnt lgkmcnt(0)
	v_add_f32_e32 v0, v0, v78
	ds_bpermute_b32 v78, v70, v0
	s_waitcnt lgkmcnt(0)
	v_add_f32_e32 v0, v0, v78
	ds_bpermute_b32 v78, v71, v0
	s_waitcnt lgkmcnt(0)
	v_add_f32_e32 v0, v0, v78
	ds_bpermute_b32 v78, v72, v0
	s_waitcnt lgkmcnt(0)
	v_add_f32_e32 v0, v0, v78
	ds_bpermute_b32 v78, v73, v0
	s_waitcnt lgkmcnt(0)
	v_add_f32_e32 v0, v0, v78
	v_fmamk_f32 v0, v0, 0x3a000000, v147
	v_cmp_gt_f32_e32 vcc, s29, v0
	v_mul_f32_e32 v78, 0x4b800000, v0
	s_nop 0
	v_cndmask_b32_e32 v0, v0, v78, vcc
	v_rsq_f32_e32 v0, v0
	s_nop 0
	v_mul_f32_e32 v78, 0x45800000, v0
	v_cndmask_b32_e32 v0, v0, v78, vcc
	v_mul_f32_e32 v2, v192, v0
	v_mul_f32_e32 v3, v193, v0
	v_mul_f32_e32 v4, v194, v0
	v_mul_f32_e32 v5, v195, v0
	v_mul_f32_e32 v2, v2, v88
	v_mul_f32_e32 v3, v3, v89
	v_mul_f32_e32 v4, v4, v90
	v_mul_f32_e32 v5, v5, v91
	v_cvt_pk_bf16_f32 v120, v2, v3
	v_cvt_pk_bf16_f32 v121, v4, v5
	global_store_dwordx2 v[30:31], v[120:121], off
	ds_write_b64 v55, v[120:121]
	v_mul_f32_e32 v2, v196, v0
	v_mul_f32_e32 v3, v197, v0
	v_mul_f32_e32 v4, v198, v0
	v_mul_f32_e32 v5, v199, v0
	v_mul_f32_e32 v2, v2, v92
	v_mul_f32_e32 v3, v3, v93
	v_mul_f32_e32 v4, v4, v94
	v_mul_f32_e32 v5, v5, v95
	v_cvt_pk_bf16_f32 v122, v2, v3
	v_cvt_pk_bf16_f32 v123, v4, v5
	global_store_dwordx2 v[30:31], v[122:123], off offset:512
	ds_write_b64 v55, v[122:123] offset:512
	v_mul_f32_e32 v2, v200, v0
	v_mul_f32_e32 v3, v201, v0
	v_mul_f32_e32 v4, v202, v0
	v_mul_f32_e32 v5, v203, v0
	v_mul_f32_e32 v2, v2, v96
	v_mul_f32_e32 v3, v3, v97
	v_mul_f32_e32 v4, v4, v98
	v_mul_f32_e32 v5, v5, v99
	v_cvt_pk_bf16_f32 v124, v2, v3
	v_cvt_pk_bf16_f32 v125, v4, v5
	global_store_dwordx2 v[30:31], v[124:125], off offset:1024
	ds_write_b64 v55, v[124:125] offset:1024
	v_mul_f32_e32 v2, v204, v0
	v_mul_f32_e32 v3, v205, v0
	v_mul_f32_e32 v4, v206, v0
	v_mul_f32_e32 v5, v207, v0
	v_mul_f32_e32 v2, v2, v100
	v_mul_f32_e32 v3, v3, v101
	v_mul_f32_e32 v4, v4, v102
	v_mul_f32_e32 v5, v5, v103
	v_cvt_pk_bf16_f32 v126, v2, v3
	v_cvt_pk_bf16_f32 v127, v4, v5
	global_store_dwordx2 v[30:31], v[126:127], off offset:1536
	ds_write_b64 v55, v[126:127] offset:1536
	v_mul_f32_e32 v2, v208, v0
	v_mul_f32_e32 v3, v209, v0
	v_mul_f32_e32 v4, v210, v0
	v_mul_f32_e32 v5, v211, v0
	v_mul_f32_e32 v2, v2, v104
	v_mul_f32_e32 v3, v3, v105
	v_mul_f32_e32 v4, v4, v106
	v_mul_f32_e32 v5, v5, v107
	v_cvt_pk_bf16_f32 v128, v2, v3
	v_cvt_pk_bf16_f32 v129, v4, v5
	global_store_dwordx2 v[30:31], v[128:129], off offset:2048
	ds_write_b64 v55, v[128:129] offset:2048
	v_mul_f32_e32 v2, v212, v0
	v_mul_f32_e32 v3, v213, v0
	v_mul_f32_e32 v4, v214, v0
	v_mul_f32_e32 v5, v215, v0
	v_mul_f32_e32 v2, v2, v108
	v_mul_f32_e32 v3, v3, v109
	v_mul_f32_e32 v4, v4, v110
	v_mul_f32_e32 v5, v5, v111
	v_cvt_pk_bf16_f32 v130, v2, v3
	v_cvt_pk_bf16_f32 v131, v4, v5
	global_store_dwordx2 v[30:31], v[130:131], off offset:2560
	ds_write_b64 v55, v[130:131] offset:2560
	v_mul_f32_e32 v2, v216, v0
	v_mul_f32_e32 v3, v217, v0
	v_mul_f32_e32 v4, v218, v0
	v_mul_f32_e32 v5, v219, v0
	v_mul_f32_e32 v2, v2, v112
	v_mul_f32_e32 v3, v3, v113
	v_mul_f32_e32 v4, v4, v114
	v_mul_f32_e32 v5, v5, v115
	v_cvt_pk_bf16_f32 v132, v2, v3
	v_cvt_pk_bf16_f32 v133, v4, v5
	global_store_dwordx2 v[30:31], v[132:133], off offset:3072
	ds_write_b64 v55, v[132:133] offset:3072
	v_mul_f32_e32 v2, v220, v0
	v_mul_f32_e32 v3, v221, v0
	v_mul_f32_e32 v4, v222, v0
	v_mul_f32_e32 v5, v223, v0
	v_mul_f32_e32 v2, v2, v116
	v_mul_f32_e32 v3, v3, v117
	v_mul_f32_e32 v4, v4, v118
	v_mul_f32_e32 v5, v5, v119
	v_cvt_pk_bf16_f32 v134, v2, v3
	v_cvt_pk_bf16_f32 v135, v4, v5
	global_store_dwordx2 v[30:31], v[134:135], off offset:3584
	ds_write_b64 v55, v[134:135] offset:3584
	s_add_u32 s0, s0, 0x1000
	s_addc_u32 s1, s1, 0
	v_add_u32_e32 v55, 0x1010, v55
	s_cmpk_eq_i32 s0, 0x4000
	s_cbranch_scc0 .Lnk_loop
	v_mov_b32_e32 v2, 0
	s_mov_b32 s0, 0
	v_mov_b64_e32 v[62:63], v[60:61]
	v_mov_b32_e32 v0, v76
	v_mov_b32_e32 v3, v2
	v_mov_b32_e32 v4, v2
	v_mov_b32_e32 v5, v2
	v_mov_b32_e32 v6, v2
	v_mov_b32_e32 v7, v2
	v_mov_b32_e32 v8, v2
	v_mov_b32_e32 v9, v2
	v_mov_b32_e32 v10, v2
	v_mov_b32_e32 v11, v2
	v_mov_b32_e32 v12, v2
	v_mov_b32_e32 v13, v2
	v_mov_b32_e32 v14, v2
	v_mov_b32_e32 v15, v2
	v_mov_b32_e32 v16, v2
	v_mov_b32_e32 v17, v2
	v_mov_b32_e32 v18, v2
	v_mov_b32_e32 v19, v2
	v_mov_b32_e32 v20, v2
	v_mov_b32_e32 v21, v2
	v_mov_b32_e32 v22, v2
	v_mov_b32_e32 v23, v2
	v_mov_b32_e32 v24, v2
	v_mov_b32_e32 v25, v2
	v_mov_b32_e32 v26, v2
	v_mov_b32_e32 v27, v2
	v_mov_b32_e32 v28, v2
	v_mov_b32_e32 v29, v2
	v_mov_b32_e32 v30, v2
	v_mov_b32_e32 v31, v2
	v_mov_b32_e32 v32, v2
	v_mov_b32_e32 v33, v2
	s_waitcnt lgkmcnt(0)
	s_barrier

.LBB2_774:
	v_readlane_b32 s0, v252, 3
	v_readlane_b32 s3, v252, 6
	s_cmp_eq_u32 s3, 38
	v_readlane_b32 s1, v252, 4
	v_readlane_b32 s2, v252, 5
	s_cbranch_scc0 .LBB2_778
	v_readlane_b32 s0, v252, 0
	v_ashrrev_i32_e32 v0, 6, v146
	s_nop 0
	v_lshl_add_u32 v0, s0, 3, v0
	s_movk_i32 s0, 0x2000
	v_cmp_gt_i32_e32 vcc, s0, v0
	s_and_saveexec_b64 s[0:1], vcc
	s_cbranch_execz .LBB2_778
	v_mbcnt_lo_u32_b32 v1, -1, 0
	v_mbcnt_hi_u32_b32 v1, -1, v1
	s_waitcnt vmcnt(0) lgkmcnt(0)
	v_and_b32_e32 v2, 64, v1
	v_add_u32_e32 v2, 64, v2
	v_xor_b32_e32 v3, 1, v1
	v_cmp_lt_i32_e32 vcc, v3, v2
	v_readlane_b32 s4, v252, 23
	v_readlane_b32 s12, v252, 31
	v_cndmask_b32_e32 v3, v1, v3, vcc
	v_lshlrev_b32_e32 v14, 2, v3
	v_xor_b32_e32 v3, 2, v1
	v_cmp_lt_i32_e32 vcc, v3, v2
	v_readlane_b32 s13, v252, 32
	v_readlane_b32 s14, v252, 33
	v_cndmask_b32_e32 v3, v1, v3, vcc
	v_lshlrev_b32_e32 v15, 2, v3
	v_xor_b32_e32 v3, 4, v1
	v_cmp_lt_i32_e32 vcc, v3, v2
	v_readlane_b32 s15, v252, 34
	v_readlane_b32 s16, v252, 35
	v_cndmask_b32_e32 v3, v1, v3, vcc
	v_lshlrev_b32_e32 v16, 2, v3
	v_xor_b32_e32 v3, 8, v1
	v_cmp_lt_i32_e32 vcc, v3, v2
	v_readlane_b32 s17, v252, 36
	v_readlane_b32 s0, v252, 1
	v_cndmask_b32_e32 v3, v1, v3, vcc
	v_lshlrev_b32_e32 v17, 2, v3
	v_xor_b32_e32 v3, 16, v1
	v_cmp_lt_i32_e32 vcc, v3, v2
	v_readlane_b32 s18, v252, 37
	v_readlane_b32 s19, v252, 38
	v_cndmask_b32_e32 v3, v1, v3, vcc
	v_lshlrev_b32_e32 v18, 2, v3
	v_xor_b32_e32 v3, 32, v1
	v_cmp_lt_i32_e32 vcc, v3, v2
	s_mov_b64 s[12:13], s[16:17]
	v_readlane_b32 s1, v252, 2
	v_cndmask_b32_e32 v1, v1, v3, vcc
	v_lshlrev_b32_e32 v19, 2, v1
	v_lshlrev_b32_e32 v1, 4, v146
	v_and_b32_e32 v12, 0x3f0, v1
	v_ashrrev_i32_e32 v1, 31, v0
	v_lshlrev_b64 v[20:21], 13, v[0:1]
	s_lshl_b32 s0, s0, 3
	v_mov_b32_e32 v13, 0
	s_mov_b64 s[14:15], s[18:19]
	v_or_b32_e32 v20, v20, v12
	v_readlane_b32 s5, v252, 24
	v_readlane_b32 s6, v252, 25
	v_lshl_add_u64 v[2:3], s[12:13], 0, v[12:13]
	v_or_b32_e32 v4, 0x1000, v12
	v_mov_b32_e32 v5, v13
	v_or_b32_e32 v6, 0x1400, v12
	v_mov_b32_e32 v7, v13
	v_or_b32_e32 v8, 0x1800, v12
	v_mov_b32_e32 v9, v13
	v_or_b32_e32 v10, 0x1c00, v12
	v_mov_b32_e32 v11, v13
	v_lshl_add_u64 v[12:13], s[14:15], 0, v[20:21]
	s_mov_b64 s[2:3], 0x1000
	s_ashr_i32 s1, s0, 31
	v_lshl_add_u64 v[4:5], s[12:13], 0, v[4:5]
	v_lshl_add_u64 v[6:7], s[12:13], 0, v[6:7]
	v_lshl_add_u64 v[8:9], s[12:13], 0, v[8:9]
	v_lshl_add_u64 v[10:11], s[12:13], 0, v[10:11]
	v_lshl_add_u64 v[12:13], v[12:13], 0, s[2:3]
	s_lshl_b64 s[2:3], s[0:1], 13
	s_mov_b64 s[4:5], 0
	v_mov_b32_e32 v1, 0x358637bd
	s_mov_b32 s1, 0x800000
	s_movk_i32 s6, 0x1fff
	v_readlane_b32 s7, v252, 26
	v_readlane_b32 s8, v252, 27
	v_readlane_b32 s9, v252, 28
	v_readlane_b32 s10, v252, 29
	v_readlane_b32 s11, v252, 30
	global_load_dwordx4 v[64:67], v[2:3], off
	global_load_dwordx4 v[68:71], v[2:3], off offset:1024
	global_load_dwordx4 v[72:75], v[2:3], off offset:2048
	global_load_dwordx4 v[76:79], v[2:3], off offset:3072
	global_load_dwordx4 v[80:83], v[4:5], off
	global_load_dwordx4 v[84:87], v[6:7], off
	global_load_dwordx4 v[88:91], v[8:9], off
	global_load_dwordx4 v[92:95], v[10:11], off
	s_cmpk_lg_u32 s0, 0x800
	s_cbranch_scc1 .Lnormf_loop1
.Lnormf_loop2:
	v_mov_b32_e32 v160, v12
	v_mov_b32_e32 v161, v13
	global_load_dwordx4 v[96:99], v[160:161], off offset:-4096
	global_load_dwordx4 v[100:103], v[160:161], off offset:-3072
	global_load_dwordx4 v[104:107], v[160:161], off offset:-2048
	global_load_dwordx4 v[108:111], v[160:161], off offset:-1024
	global_load_dwordx4 v[112:115], v[160:161], off
	global_load_dwordx4 v[116:119], v[160:161], off offset:1024
	global_load_dwordx4 v[120:123], v[160:161], off offset:2048
	global_load_dwordx4 v[124:127], v[160:161], off offset:3072
	v_lshl_add_u64 v[162:163], v[160:161], 0, s[2:3]
	global_load_dwordx4 v[128:131], v[162:163], off offset:-4096
	global_load_dwordx4 v[132:135], v[162:163], off offset:-3072
	global_load_dwordx4 v[136:139], v[162:163], off offset:-2048
	global_load_dwordx4 v[140:143], v[162:163], off offset:-1024
	global_load_dwordx4 v[144:147], v[162:163], off
	global_load_dwordx4 v[148:151], v[162:163], off offset:1024
	global_load_dwordx4 v[152:155], v[162:163], off offset:2048
	global_load_dwordx4 v[156:159], v[162:163], off offset:3072
	v_lshl_add_u64 v[12:13], v[162:163], 0, s[2:3]
	v_add_u32_e32 v0, s0, v0
	v_add_u32_e32 v0, s0, v0
	s_waitcnt vmcnt(8)
	v_mul_f32_e32 v164, v96, v96
	v_mul_f32_e32 v165, v98, v98
	v_fmac_f32_e32 v164, v97, v97
	v_fmac_f32_e32 v165, v99, v99
	v_add_f32_e32 v56, v164, v165
	v_mul_f32_e32 v164, v100, v100
	v_mul_f32_e32 v165, v102, v102
	v_fmac_f32_e32 v164, v101, v101
	v_fmac_f32_e32 v165, v103, v103
	v_add_f32_e32 v164, v164, v165
	v_add_f32_e32 v56, v56, v164
	v_mul_f32_e32 v164, v104, v104
	v_mul_f32_e32 v165, v106, v106
	v_fmac_f32_e32 v164, v105, v105
	v_fmac_f32_e32 v165, v107, v107
	v_add_f32_e32 v164, v164, v165
	v_add_f32_e32 v56, v56, v164
	v_mul_f32_e32 v164, v108, v108
	v_mul_f32_e32 v165, v110, v110
	v_fmac_f32_e32 v164, v109, v109
	v_fmac_f32_e32 v165, v111, v111
	v_add_f32_e32 v164, v164, v165
	v_add_f32_e32 v56, v56, v164
	v_mul_f32_e32 v164, v112, v112
	v_mul_f32_e32 v165, v114, v114
	v_fmac_f32_e32 v164, v113, v113
	v_fmac_f32_e32 v165, v115, v115
	v_add_f32_e32 v164, v164, v165
	v_add_f32_e32 v56, v56, v164
	v_mul_f32_e32 v164, v116, v116
	v_mul_f32_e32 v165, v118, v118
	v_fmac_f32_e32 v164, v117, v117
	v_fmac_f32_e32 v165, v119, v119
	v_add_f32_e32 v164, v164, v165
	v_add_f32_e32 v56, v56, v164
	v_mul_f32_e32 v164, v120, v120
	v_mul_f32_e32 v165, v122, v122
	v_fmac_f32_e32 v164, v121, v121
	v_fmac_f32_e32 v165, v123, v123
	v_add_f32_e32 v164, v164, v165
	v_add_f32_e32 v56, v56, v164
	v_mul_f32_e32 v164, v124, v124
	v_mul_f32_e32 v165, v126, v126
	v_fmac_f32_e32 v164, v125, v125
	v_fmac_f32_e32 v165, v127, v127
	v_add_f32_e32 v164, v164, v165
	v_add_f32_e32 v56, v56, v164
	ds_bpermute_b32 v57, v14, v56
	s_waitcnt lgkmcnt(0)
	v_add_f32_e32 v56, v56, v57
	ds_bpermute_b32 v57, v15, v56
	s_waitcnt lgkmcnt(0)
	v_add_f32_e32 v56, v56, v57
	ds_bpermute_b32 v57, v16, v56
	s_waitcnt lgkmcnt(0)
	v_add_f32_e32 v56, v56, v57
	ds_bpermute_b32 v57, v17, v56
	s_waitcnt lgkmcnt(0)
	v_add_f32_e32 v56, v56, v57
	ds_bpermute_b32 v57, v18, v56
	s_waitcnt lgkmcnt(0)
	v_add_f32_e32 v56, v56, v57
	ds_bpermute_b32 v57, v19, v56
	s_waitcnt lgkmcnt(0)
	v_add_f32_e32 v56, v56, v57
	v_fmamk_f32 v56, v56, 0x3a000000, v1
	v_mul_f32_e32 v57, 0x4b800000, v56
	v_cmp_gt_f32_e32 vcc, s1, v56
	s_nop 1
	v_cndmask_b32_e32 v56, v56, v57, vcc
	v_rsq_f32_e32 v56, v56
	s_nop 0
	v_mul_f32_e32 v57, 0x45800000, v56
	v_cndmask_b32_e32 v56, v56, v57, vcc
	v_mul_f32_e32 v96, v96, v56
	v_mul_f32_e32 v97, v97, v56
	v_mul_f32_e32 v98, v98, v56
	v_mul_f32_e32 v99, v99, v56
	v_mul_f32_e32 v96, v64, v96
	v_mul_f32_e32 v97, v65, v97
	v_mul_f32_e32 v98, v66, v98
	v_mul_f32_e32 v99, v67, v99
	global_store_dwordx4 v[160:161], v[96:99], off offset:-4096
	v_mul_f32_e32 v100, v100, v56
	v_mul_f32_e32 v101, v101, v56
	v_mul_f32_e32 v102, v102, v56
	v_mul_f32_e32 v103, v103, v56
	v_mul_f32_e32 v100, v68, v100
	v_mul_f32_e32 v101, v69, v101
	v_mul_f32_e32 v102, v70, v102
	v_mul_f32_e32 v103, v71, v103
	global_store_dwordx4 v[160:161], v[100:103], off offset:-3072
	v_mul_f32_e32 v104, v104, v56
	v_mul_f32_e32 v105, v105, v56
	v_mul_f32_e32 v106, v106, v56
	v_mul_f32_e32 v107, v107, v56
	v_mul_f32_e32 v104, v72, v104
	v_mul_f32_e32 v105, v73, v105
	v_mul_f32_e32 v106, v74, v106
	v_mul_f32_e32 v107, v75, v107
	global_store_dwordx4 v[160:161], v[104:107], off offset:-2048
	v_mul_f32_e32 v108, v108, v56
	v_mul_f32_e32 v109, v109, v56
	v_mul_f32_e32 v110, v110, v56
	v_mul_f32_e32 v111, v111, v56
	v_mul_f32_e32 v108, v76, v108
	v_mul_f32_e32 v109, v77, v109
	v_mul_f32_e32 v110, v78, v110
	v_mul_f32_e32 v111, v79, v111
	global_store_dwordx4 v[160:161], v[108:111], off offset:-1024
	v_mul_f32_e32 v112, v112, v56
	v_mul_f32_e32 v113, v113, v56
	v_mul_f32_e32 v114, v114, v56
	v_mul_f32_e32 v115, v115, v56
	v_mul_f32_e32 v112, v80, v112
	v_mul_f32_e32 v113, v81, v113
	v_mul_f32_e32 v114, v82, v114
	v_mul_f32_e32 v115, v83, v115
	global_store_dwordx4 v[160:161], v[112:115], off
	v_mul_f32_e32 v116, v116, v56
	v_mul_f32_e32 v117, v117, v56
	v_mul_f32_e32 v118, v118, v56
	v_mul_f32_e32 v119, v119, v56
	v_mul_f32_e32 v116, v84, v116
	v_mul_f32_e32 v117, v85, v117
	v_mul_f32_e32 v118, v86, v118
	v_mul_f32_e32 v119, v87, v119
	global_store_dwordx4 v[160:161], v[116:119], off offset:1024
	v_mul_f32_e32 v120, v120, v56
	v_mul_f32_e32 v121, v121, v56
	v_mul_f32_e32 v122, v122, v56
	v_mul_f32_e32 v123, v123, v56
	v_mul_f32_e32 v120, v88, v120
	v_mul_f32_e32 v121, v89, v121
	v_mul_f32_e32 v122, v90, v122
	v_mul_f32_e32 v123, v91, v123
	global_store_dwordx4 v[160:161], v[120:123], off offset:2048
	v_mul_f32_e32 v124, v124, v56
	v_mul_f32_e32 v125, v125, v56
	v_mul_f32_e32 v126, v126, v56
	v_mul_f32_e32 v127, v127, v56
	v_mul_f32_e32 v124, v92, v124
	v_mul_f32_e32 v125, v93, v125
	v_mul_f32_e32 v126, v94, v126
	v_mul_f32_e32 v127, v95, v127
	global_store_dwordx4 v[160:161], v[124:127], off offset:3072
	s_waitcnt vmcnt(8)
	v_mul_f32_e32 v164, v128, v128
	v_mul_f32_e32 v165, v130, v130
	v_fmac_f32_e32 v164, v129, v129
	v_fmac_f32_e32 v165, v131, v131
	v_add_f32_e32 v56, v164, v165
	v_mul_f32_e32 v164, v132, v132
	v_mul_f32_e32 v165, v134, v134
	v_fmac_f32_e32 v164, v133, v133
	v_fmac_f32_e32 v165, v135, v135
	v_add_f32_e32 v164, v164, v165
	v_add_f32_e32 v56, v56, v164
	v_mul_f32_e32 v164, v136, v136
	v_mul_f32_e32 v165, v138, v138
	v_fmac_f32_e32 v164, v137, v137
	v_fmac_f32_e32 v165, v139, v139
	v_add_f32_e32 v164, v164, v165
	v_add_f32_e32 v56, v56, v164
	v_mul_f32_e32 v164, v140, v140
	v_mul_f32_e32 v165, v142, v142
	v_fmac_f32_e32 v164, v141, v141
	v_fmac_f32_e32 v165, v143, v143
	v_add_f32_e32 v164, v164, v165
	v_add_f32_e32 v56, v56, v164
	v_mul_f32_e32 v164, v144, v144
	v_mul_f32_e32 v165, v146, v146
	v_fmac_f32_e32 v164, v145, v145
	v_fmac_f32_e32 v165, v147, v147
	v_add_f32_e32 v164, v164, v165
	v_add_f32_e32 v56, v56, v164
	v_mul_f32_e32 v164, v148, v148
	v_mul_f32_e32 v165, v150, v150
	v_fmac_f32_e32 v164, v149, v149
	v_fmac_f32_e32 v165, v151, v151
	v_add_f32_e32 v164, v164, v165
	v_add_f32_e32 v56, v56, v164
	v_mul_f32_e32 v164, v152, v152
	v_mul_f32_e32 v165, v154, v154
	v_fmac_f32_e32 v164, v153, v153
	v_fmac_f32_e32 v165, v155, v155
	v_add_f32_e32 v164, v164, v165
	v_add_f32_e32 v56, v56, v164
	v_mul_f32_e32 v164, v156, v156
	v_mul_f32_e32 v165, v158, v158
	v_fmac_f32_e32 v164, v157, v157
	v_fmac_f32_e32 v165, v159, v159
	v_add_f32_e32 v164, v164, v165
	v_add_f32_e32 v56, v56, v164
	ds_bpermute_b32 v57, v14, v56
	s_waitcnt lgkmcnt(0)
	v_add_f32_e32 v56, v56, v57
	ds_bpermute_b32 v57, v15, v56
	s_waitcnt lgkmcnt(0)
	v_add_f32_e32 v56, v56, v57
	ds_bpermute_b32 v57, v16, v56
	s_waitcnt lgkmcnt(0)
	v_add_f32_e32 v56, v56, v57
	ds_bpermute_b32 v57, v17, v56
	s_waitcnt lgkmcnt(0)
	v_add_f32_e32 v56, v56, v57
	ds_bpermute_b32 v57, v18, v56
	s_waitcnt lgkmcnt(0)
	v_add_f32_e32 v56, v56, v57
	ds_bpermute_b32 v57, v19, v56
	s_waitcnt lgkmcnt(0)
	v_add_f32_e32 v56, v56, v57
	v_fmamk_f32 v56, v56, 0x3a000000, v1
	v_mul_f32_e32 v57, 0x4b800000, v56
	v_cmp_gt_f32_e32 vcc, s1, v56
	s_nop 1
	v_cndmask_b32_e32 v56, v56, v57, vcc
	v_rsq_f32_e32 v56, v56
	s_nop 0
	v_mul_f32_e32 v57, 0x45800000, v56
	v_cndmask_b32_e32 v56, v56, v57, vcc
	v_mul_f32_e32 v128, v128, v56
	v_mul_f32_e32 v129, v129, v56
	v_mul_f32_e32 v130, v130, v56
	v_mul_f32_e32 v131, v131, v56
	v_mul_f32_e32 v128, v64, v128
	v_mul_f32_e32 v129, v65, v129
	v_mul_f32_e32 v130, v66, v130
	v_mul_f32_e32 v131, v67, v131
	global_store_dwordx4 v[162:163], v[128:131], off offset:-4096
	v_mul_f32_e32 v132, v132, v56
	v_mul_f32_e32 v133, v133, v56
	v_mul_f32_e32 v134, v134, v56
	v_mul_f32_e32 v135, v135, v56
	v_mul_f32_e32 v132, v68, v132
	v_mul_f32_e32 v133, v69, v133
	v_mul_f32_e32 v134, v70, v134
	v_mul_f32_e32 v135, v71, v135
	global_store_dwordx4 v[162:163], v[132:135], off offset:-3072
	v_mul_f32_e32 v136, v136, v56
	v_mul_f32_e32 v137, v137, v56
	v_mul_f32_e32 v138, v138, v56
	v_mul_f32_e32 v139, v139, v56
	v_mul_f32_e32 v136, v72, v136
	v_mul_f32_e32 v137, v73, v137
	v_mul_f32_e32 v138, v74, v138
	v_mul_f32_e32 v139, v75, v139
	global_store_dwordx4 v[162:163], v[136:139], off offset:-2048
	v_mul_f32_e32 v140, v140, v56
	v_mul_f32_e32 v141, v141, v56
	v_mul_f32_e32 v142, v142, v56
	v_mul_f32_e32 v143, v143, v56
	v_mul_f32_e32 v140, v76, v140
	v_mul_f32_e32 v141, v77, v141
	v_mul_f32_e32 v142, v78, v142
	v_mul_f32_e32 v143, v79, v143
	global_store_dwordx4 v[162:163], v[140:143], off offset:-1024
	v_mul_f32_e32 v144, v144, v56
	v_mul_f32_e32 v145, v145, v56
	v_mul_f32_e32 v146, v146, v56
	v_mul_f32_e32 v147, v147, v56
	v_mul_f32_e32 v144, v80, v144
	v_mul_f32_e32 v145, v81, v145
	v_mul_f32_e32 v146, v82, v146
	v_mul_f32_e32 v147, v83, v147
	global_store_dwordx4 v[162:163], v[144:147], off
	v_mul_f32_e32 v148, v148, v56
	v_mul_f32_e32 v149, v149, v56
	v_mul_f32_e32 v150, v150, v56
	v_mul_f32_e32 v151, v151, v56
	v_mul_f32_e32 v148, v84, v148
	v_mul_f32_e32 v149, v85, v149
	v_mul_f32_e32 v150, v86, v150
	v_mul_f32_e32 v151, v87, v151
	global_store_dwordx4 v[162:163], v[148:151], off offset:1024
	v_mul_f32_e32 v152, v152, v56
	v_mul_f32_e32 v153, v153, v56
	v_mul_f32_e32 v154, v154, v56
	v_mul_f32_e32 v155, v155, v56
	v_mul_f32_e32 v152, v88, v152
	v_mul_f32_e32 v153, v89, v153
	v_mul_f32_e32 v154, v90, v154
	v_mul_f32_e32 v155, v91, v155
	global_store_dwordx4 v[162:163], v[152:155], off offset:2048
	v_mul_f32_e32 v156, v156, v56
	v_mul_f32_e32 v157, v157, v56
	v_mul_f32_e32 v158, v158, v56
	v_mul_f32_e32 v159, v159, v56
	v_mul_f32_e32 v156, v92, v156
	v_mul_f32_e32 v157, v93, v157
	v_mul_f32_e32 v158, v94, v158
	v_mul_f32_e32 v159, v95, v159
	global_store_dwordx4 v[162:163], v[156:159], off offset:3072
	v_cmp_lt_i32_e32 vcc, s6, v0
	s_or_b64 s[4:5], vcc, s[4:5]
	s_andn2_b64 exec, exec, s[4:5]
	s_cbranch_execnz .Lnormf_loop2
	s_branch .Lnormf_done
.Lnormf_loop1:
	global_load_dwordx4 v[96:99], v[12:13], off offset:-4096
	global_load_dwordx4 v[100:103], v[12:13], off offset:-3072
	global_load_dwordx4 v[104:107], v[12:13], off offset:-2048
	global_load_dwordx4 v[108:111], v[12:13], off offset:-1024
	global_load_dwordx4 v[112:115], v[12:13], off
	global_load_dwordx4 v[116:119], v[12:13], off offset:1024
	global_load_dwordx4 v[120:123], v[12:13], off offset:2048
	global_load_dwordx4 v[124:127], v[12:13], off offset:3072
	v_add_u32_e32 v0, s0, v0
	s_waitcnt vmcnt(0)
	v_mul_f32_e32 v164, v96, v96
	v_mul_f32_e32 v165, v98, v98
	v_fmac_f32_e32 v164, v97, v97
	v_fmac_f32_e32 v165, v99, v99
	v_add_f32_e32 v56, v164, v165
	v_mul_f32_e32 v164, v100, v100
	v_mul_f32_e32 v165, v102, v102
	v_fmac_f32_e32 v164, v101, v101
	v_fmac_f32_e32 v165, v103, v103
	v_add_f32_e32 v164, v164, v165
	v_add_f32_e32 v56, v56, v164
	v_mul_f32_e32 v164, v104, v104
	v_mul_f32_e32 v165, v106, v106
	v_fmac_f32_e32 v164, v105, v105
	v_fmac_f32_e32 v165, v107, v107
	v_add_f32_e32 v164, v164, v165
	v_add_f32_e32 v56, v56, v164
	v_mul_f32_e32 v164, v108, v108
	v_mul_f32_e32 v165, v110, v110
	v_fmac_f32_e32 v164, v109, v109
	v_fmac_f32_e32 v165, v111, v111
	v_add_f32_e32 v164, v164, v165
	v_add_f32_e32 v56, v56, v164
	v_mul_f32_e32 v164, v112, v112
	v_mul_f32_e32 v165, v114, v114
	v_fmac_f32_e32 v164, v113, v113
	v_fmac_f32_e32 v165, v115, v115
	v_add_f32_e32 v164, v164, v165
	v_add_f32_e32 v56, v56, v164
	v_mul_f32_e32 v164, v116, v116
	v_mul_f32_e32 v165, v118, v118
	v_fmac_f32_e32 v164, v117, v117
	v_fmac_f32_e32 v165, v119, v119
	v_add_f32_e32 v164, v164, v165
	v_add_f32_e32 v56, v56, v164
	v_mul_f32_e32 v164, v120, v120
	v_mul_f32_e32 v165, v122, v122
	v_fmac_f32_e32 v164, v121, v121
	v_fmac_f32_e32 v165, v123, v123
	v_add_f32_e32 v164, v164, v165
	v_add_f32_e32 v56, v56, v164
	v_mul_f32_e32 v164, v124, v124
	v_mul_f32_e32 v165, v126, v126
	v_fmac_f32_e32 v164, v125, v125
	v_fmac_f32_e32 v165, v127, v127
	v_add_f32_e32 v164, v164, v165
	v_add_f32_e32 v56, v56, v164
	ds_bpermute_b32 v57, v14, v56
	s_waitcnt lgkmcnt(0)
	v_add_f32_e32 v56, v56, v57
	ds_bpermute_b32 v57, v15, v56
	s_waitcnt lgkmcnt(0)
	v_add_f32_e32 v56, v56, v57
	ds_bpermute_b32 v57, v16, v56
	s_waitcnt lgkmcnt(0)
	v_add_f32_e32 v56, v56, v57
	ds_bpermute_b32 v57, v17, v56
	s_waitcnt lgkmcnt(0)
	v_add_f32_e32 v56, v56, v57
	ds_bpermute_b32 v57, v18, v56
	s_waitcnt lgkmcnt(0)
	v_add_f32_e32 v56, v56, v57
	ds_bpermute_b32 v57, v19, v56
	s_waitcnt lgkmcnt(0)
	v_add_f32_e32 v56, v56, v57
	v_fmamk_f32 v56, v56, 0x3a000000, v1
	v_mul_f32_e32 v57, 0x4b800000, v56
	v_cmp_gt_f32_e32 vcc, s1, v56
	s_nop 1
	v_cndmask_b32_e32 v56, v56, v57, vcc
	v_rsq_f32_e32 v56, v56
	s_nop 0
	v_mul_f32_e32 v57, 0x45800000, v56
	v_cndmask_b32_e32 v56, v56, v57, vcc
	v_mul_f32_e32 v96, v96, v56
	v_mul_f32_e32 v97, v97, v56
	v_mul_f32_e32 v98, v98, v56
	v_mul_f32_e32 v99, v99, v56
	v_mul_f32_e32 v96, v64, v96
	v_mul_f32_e32 v97, v65, v97
	v_mul_f32_e32 v98, v66, v98
	v_mul_f32_e32 v99, v67, v99
	global_store_dwordx4 v[12:13], v[96:99], off offset:-4096
	v_mul_f32_e32 v100, v100, v56
	v_mul_f32_e32 v101, v101, v56
	v_mul_f32_e32 v102, v102, v56
	v_mul_f32_e32 v103, v103, v56
	v_mul_f32_e32 v100, v68, v100
	v_mul_f32_e32 v101, v69, v101
	v_mul_f32_e32 v102, v70, v102
	v_mul_f32_e32 v103, v71, v103
	global_store_dwordx4 v[12:13], v[100:103], off offset:-3072
	v_mul_f32_e32 v104, v104, v56
	v_mul_f32_e32 v105, v105, v56
	v_mul_f32_e32 v106, v106, v56
	v_mul_f32_e32 v107, v107, v56
	v_mul_f32_e32 v104, v72, v104
	v_mul_f32_e32 v105, v73, v105
	v_mul_f32_e32 v106, v74, v106
	v_mul_f32_e32 v107, v75, v107
	global_store_dwordx4 v[12:13], v[104:107], off offset:-2048
	v_mul_f32_e32 v108, v108, v56
	v_mul_f32_e32 v109, v109, v56
	v_mul_f32_e32 v110, v110, v56
	v_mul_f32_e32 v111, v111, v56
	v_mul_f32_e32 v108, v76, v108
	v_mul_f32_e32 v109, v77, v109
	v_mul_f32_e32 v110, v78, v110
	v_mul_f32_e32 v111, v79, v111
	global_store_dwordx4 v[12:13], v[108:111], off offset:-1024
	v_mul_f32_e32 v112, v112, v56
	v_mul_f32_e32 v113, v113, v56
	v_mul_f32_e32 v114, v114, v56
	v_mul_f32_e32 v115, v115, v56
	v_mul_f32_e32 v112, v80, v112
	v_mul_f32_e32 v113, v81, v113
	v_mul_f32_e32 v114, v82, v114
	v_mul_f32_e32 v115, v83, v115
	global_store_dwordx4 v[12:13], v[112:115], off
	v_mul_f32_e32 v116, v116, v56
	v_mul_f32_e32 v117, v117, v56
	v_mul_f32_e32 v118, v118, v56
	v_mul_f32_e32 v119, v119, v56
	v_mul_f32_e32 v116, v84, v116
	v_mul_f32_e32 v117, v85, v117
	v_mul_f32_e32 v118, v86, v118
	v_mul_f32_e32 v119, v87, v119
	global_store_dwordx4 v[12:13], v[116:119], off offset:1024
	v_mul_f32_e32 v120, v120, v56
	v_mul_f32_e32 v121, v121, v56
	v_mul_f32_e32 v122, v122, v56
	v_mul_f32_e32 v123, v123, v56
	v_mul_f32_e32 v120, v88, v120
	v_mul_f32_e32 v121, v89, v121
	v_mul_f32_e32 v122, v90, v122
	v_mul_f32_e32 v123, v91, v123
	global_store_dwordx4 v[12:13], v[120:123], off offset:2048
	v_mul_f32_e32 v124, v124, v56
	v_mul_f32_e32 v125, v125, v56
	v_mul_f32_e32 v126, v126, v56
	v_mul_f32_e32 v127, v127, v56
	v_mul_f32_e32 v124, v92, v124
	v_mul_f32_e32 v125, v93, v125
	v_mul_f32_e32 v126, v94, v126
	v_mul_f32_e32 v127, v95, v127
	global_store_dwordx4 v[12:13], v[124:127], off offset:3072
	v_cmp_lt_i32_e32 vcc, s6, v0
	s_or_b64 s[4:5], vcc, s[4:5]
	v_lshl_add_u64 v[12:13], v[12:13], 0, s[2:3]
	s_andn2_b64 exec, exec, s[4:5]
	s_cbranch_execnz .Lnormf_loop1
.Lnormf_done:
.LBB2_778:
	s_endpgm
